# P7 K-loop: one small load per wave and iteration touching the x1 rows the epilogue reads (cache fill only), retried now that the epilogue loads allocate in L2
# baseline (speedup 1.0000x reference)
.LBB0_940:
	s_add_u32 s24, s22, 0x100
	s_addc_u32 s25, s23, 0
	s_cmpk_eq_i32 s56, 0x54
	s_cselect_b32 s29, s19, s25
	s_cselect_b32 s28, s18, s24
	s_cselect_b32 s27, s21, s47
	s_cselect_b32 s26, s20, s46
	s_and_b64 vcc, exec, s[12:13]
	s_cbranch_vccz .Lk64_trail_p7
	s_sub_u32 vcc_lo, s46, 0x80
	s_subb_u32 vcc_hi, s47, 0
	s_add_i32 m0, s30, 0x18000
	s_nop 0
	global_load_lds_dwordx4 v130, vcc
	s_add_i32 m0, s30, 0x1a000
	s_nop 0
	global_load_lds_dwordx4 v134, vcc
	s_add_u32 vcc_lo, vcc_lo, 0x58000
	s_addc_u32 vcc_hi, vcc_hi, 0
	s_add_i32 m0, s30, 0x19000
	s_nop 0
	global_load_lds_dwordx4 v130, vcc
	s_add_i32 m0, s30, 0x1b000
	s_nop 0
	global_load_lds_dwordx4 v134, vcc
	s_add_u32 vcc_lo, vcc_lo, 0x108000
	s_addc_u32 vcc_hi, vcc_hi, 0
	s_add_i32 m0, s30, 0x1c000
	s_nop 0
	global_load_lds_dwordx4 v130, vcc
	s_add_i32 m0, s30, 0x1e000
	s_nop 0
	global_load_lds_dwordx4 v134, vcc
	s_add_u32 vcc_lo, vcc_lo, 0x58000
	s_addc_u32 vcc_hi, vcc_hi, 0
	s_add_i32 m0, s30, 0x1d000
	s_nop 0
	global_load_lds_dwordx4 v130, vcc
	s_add_i32 m0, s30, 0x1f000
	s_nop 0
	global_load_lds_dwordx4 v134, vcc
	s_add_i32 vcc_lo, s56, -22
	s_and_b32 vcc_lo, vcc_lo, 62
	s_lshl_b32 vcc_lo, vcc_lo, 2
	s_lshr_b32 vcc_hi, s30, 10
	s_add_i32 vcc_lo, vcc_lo, vcc_hi
	s_lshl_b32 vcc_hi, s54, 8
	s_add_i32 vcc_lo, vcc_lo, vcc_hi
	s_lshl_b32 vcc_lo, vcc_lo, 13
	s_lshl_b32 vcc_hi, s55, 10
	s_add_i32 vcc_lo, vcc_lo, vcc_hi
	s_add_u32 vcc_lo, s14, vcc_lo
	s_addc_u32 vcc_hi, s15, 0
	v_and_b32_e32 v248, 15, v252
	v_lshlrev_b32_e32 v248, 6, v248
	s_lshr_b32 m0, s30, 2
	s_add_i32 m0, m0, 0x20000
	s_nop 0
	global_load_lds_dword v248, vcc
	ds_read_b128 v[144:147], v185 offset:0
	ds_read_b128 v[148:151], v185 offset:1024
	ds_read_b128 v[152:155], v185 offset:2048
	ds_read_b128 v[156:159], v185 offset:3072
	ds_read_b128 v[160:163], v186 offset:0
	ds_read_b128 v[164:167], v186 offset:1024
	ds_read_b128 v[168:171], v186 offset:2048
	ds_read_b128 v[172:175], v186 offset:3072
	ds_read_b128 v[176:179], v187 offset:0
	ds_read_b128 v[190:193], v187 offset:1024
	ds_read_b128 v[194:197], v187 offset:2048
	ds_read_b128 v[198:201], v187 offset:3072
	ds_read_b128 v[202:205], v187 offset:4096
	ds_read_b128 v[206:209], v187 offset:5120
	ds_read_b128 v[210:213], v187 offset:6144
	ds_read_b128 v[214:217], v187 offset:7168
	ds_read_b128 v[220:223], v187 offset:16384
	ds_read_b128 v[224:227], v187 offset:17408
	ds_read_b128 v[228:231], v187 offset:18432
	ds_read_b128 v[232:235], v187 offset:19456
	ds_read_b128 v[236:239], v187 offset:20480
	ds_read_b128 v[240:243], v187 offset:21504
	ds_read_b128 v[244:247], v187 offset:22528
	ds_read_b128 v[248:251], v187 offset:23552
	s_nop 15
	s_nop 15
	s_waitcnt lgkmcnt(0)
	s_barrier
	s_setprio 1
	v_mfma_f32_16x16x32_bf16 v[72:75], v[144:147], v[176:179], v[72:75]
	v_mfma_f32_16x16x32_bf16 v[76:79], v[152:155], v[176:179], v[76:79]
	v_mfma_f32_16x16x32_bf16 v[96:99], v[144:147], v[194:197], v[96:99]
	v_mfma_f32_16x16x32_bf16 v[100:103], v[152:155], v[194:197], v[100:103]
	v_mfma_f32_16x16x32_bf16 v[120:123], v[144:147], v[202:205], v[120:123]
	v_mfma_f32_16x16x32_bf16 v[124:127], v[152:155], v[202:205], v[124:127]
	v_mfma_f32_16x16x32_bf16 v[92:95], v[144:147], v[210:213], v[92:95]
	v_mfma_f32_16x16x32_bf16 v[84:87], v[152:155], v[210:213], v[84:87]
	v_mfma_f32_16x16x32_bf16 v[72:75], v[148:151], v[190:193], v[72:75]
	v_mfma_f32_16x16x32_bf16 v[76:79], v[156:159], v[190:193], v[76:79]
	v_mfma_f32_16x16x32_bf16 v[96:99], v[148:151], v[198:201], v[96:99]
	v_mfma_f32_16x16x32_bf16 v[100:103], v[156:159], v[198:201], v[100:103]
	v_mfma_f32_16x16x32_bf16 v[120:123], v[148:151], v[206:209], v[120:123]
	v_mfma_f32_16x16x32_bf16 v[124:127], v[156:159], v[206:209], v[124:127]
	v_mfma_f32_16x16x32_bf16 v[92:95], v[148:151], v[214:217], v[92:95]
	v_mfma_f32_16x16x32_bf16 v[84:87], v[156:159], v[214:217], v[84:87]
	s_setprio 0
	s_setprio 1
	v_mfma_f32_16x16x32_bf16 v[80:83], v[160:163], v[176:179], v[80:83]
	v_mfma_f32_16x16x32_bf16 v[88:91], v[168:171], v[176:179], v[88:91]
	v_mfma_f32_16x16x32_bf16 v[108:111], v[160:163], v[194:197], v[108:111]
	v_mfma_f32_16x16x32_bf16 v[112:115], v[168:171], v[194:197], v[112:115]
	v_mfma_f32_16x16x32_bf16 v[116:119], v[160:163], v[202:205], v[116:119]
	v_mfma_f32_16x16x32_bf16 v[104:107], v[168:171], v[202:205], v[104:107]
	v_mfma_f32_16x16x32_bf16 v[68:71], v[160:163], v[210:213], v[68:71]
	v_mfma_f32_16x16x32_bf16 v[64:67], v[168:171], v[210:213], v[64:67]
	v_mfma_f32_16x16x32_bf16 v[80:83], v[164:167], v[190:193], v[80:83]
	v_mfma_f32_16x16x32_bf16 v[88:91], v[172:175], v[190:193], v[88:91]
	v_mfma_f32_16x16x32_bf16 v[108:111], v[164:167], v[198:201], v[108:111]
	v_mfma_f32_16x16x32_bf16 v[112:115], v[172:175], v[198:201], v[112:115]
	v_mfma_f32_16x16x32_bf16 v[116:119], v[164:167], v[206:209], v[116:119]
	v_mfma_f32_16x16x32_bf16 v[104:107], v[172:175], v[206:209], v[104:107]
	v_mfma_f32_16x16x32_bf16 v[68:71], v[164:167], v[214:217], v[68:71]
	v_mfma_f32_16x16x32_bf16 v[64:67], v[172:175], v[214:217], v[64:67]
	s_setprio 0
	s_setprio 1
	v_mfma_f32_16x16x32_bf16 v[60:63], v[144:147], v[220:223], v[60:63]
	v_mfma_f32_16x16x32_bf16 v[56:59], v[152:155], v[220:223], v[56:59]
	v_mfma_f32_16x16x32_bf16 v[44:47], v[144:147], v[228:231], v[44:47]
	v_mfma_f32_16x16x32_bf16 v[40:43], v[152:155], v[228:231], v[40:43]
	v_mfma_f32_16x16x32_bf16 v[28:31], v[144:147], v[236:239], v[28:31]
	v_mfma_f32_16x16x32_bf16 v[24:27], v[152:155], v[236:239], v[24:27]
	v_mfma_f32_16x16x32_bf16 v[12:15], v[144:147], v[244:247], v[12:15]
	v_mfma_f32_16x16x32_bf16 v[8:11], v[152:155], v[244:247], v[8:11]
	v_mfma_f32_16x16x32_bf16 v[60:63], v[148:151], v[224:227], v[60:63]
	v_mfma_f32_16x16x32_bf16 v[56:59], v[156:159], v[224:227], v[56:59]
	v_mfma_f32_16x16x32_bf16 v[44:47], v[148:151], v[232:235], v[44:47]
	v_mfma_f32_16x16x32_bf16 v[40:43], v[156:159], v[232:235], v[40:43]
	v_mfma_f32_16x16x32_bf16 v[28:31], v[148:151], v[240:243], v[28:31]
	v_mfma_f32_16x16x32_bf16 v[24:27], v[156:159], v[240:243], v[24:27]
	v_mfma_f32_16x16x32_bf16 v[12:15], v[148:151], v[248:251], v[12:15]
	v_mfma_f32_16x16x32_bf16 v[8:11], v[156:159], v[248:251], v[8:11]
	s_setprio 0
	s_setprio 1
	v_mfma_f32_16x16x32_bf16 v[52:55], v[160:163], v[220:223], v[52:55]
	v_mfma_f32_16x16x32_bf16 v[48:51], v[168:171], v[220:223], v[48:51]
	v_mfma_f32_16x16x32_bf16 v[36:39], v[160:163], v[228:231], v[36:39]
	v_mfma_f32_16x16x32_bf16 v[32:35], v[168:171], v[228:231], v[32:35]
	v_mfma_f32_16x16x32_bf16 v[20:23], v[160:163], v[236:239], v[20:23]
	v_mfma_f32_16x16x32_bf16 v[16:19], v[168:171], v[236:239], v[16:19]
	v_mfma_f32_16x16x32_bf16 v[4:7], v[160:163], v[244:247], v[4:7]
	v_mfma_f32_16x16x32_bf16 v[0:3], v[168:171], v[244:247], v[0:3]
	v_mfma_f32_16x16x32_bf16 v[52:55], v[164:167], v[224:227], v[52:55]
	v_mfma_f32_16x16x32_bf16 v[48:51], v[172:175], v[224:227], v[48:51]
	v_mfma_f32_16x16x32_bf16 v[36:39], v[164:167], v[232:235], v[36:39]
	v_mfma_f32_16x16x32_bf16 v[32:35], v[172:175], v[232:235], v[32:35]
	v_mfma_f32_16x16x32_bf16 v[20:23], v[164:167], v[240:243], v[20:23]
	v_mfma_f32_16x16x32_bf16 v[16:19], v[172:175], v[240:243], v[16:19]
	v_mfma_f32_16x16x32_bf16 v[4:7], v[164:167], v[248:251], v[4:7]
	v_mfma_f32_16x16x32_bf16 v[0:3], v[172:175], v[248:251], v[0:3]
	s_setprio 0
	s_waitcnt vmcnt(1)
	s_barrier
	s_add_u32 vcc_lo, s26, 0x0
	s_addc_u32 vcc_hi, s27, 0
	s_add_i32 m0, s30, 0x10000
	s_nop 0
	global_load_lds_dwordx4 v130, vcc
	s_add_i32 m0, s30, 0x12000
	s_nop 0
	global_load_lds_dwordx4 v134, vcc
	s_add_u32 vcc_lo, vcc_lo, 0x58000
	s_addc_u32 vcc_hi, vcc_hi, 0
	s_add_i32 m0, s30, 0x11000
	s_nop 0
	global_load_lds_dwordx4 v130, vcc
	s_add_i32 m0, s30, 0x13000
	s_nop 0
	global_load_lds_dwordx4 v134, vcc
	s_add_u32 vcc_lo, vcc_lo, 0x108000
	s_addc_u32 vcc_hi, vcc_hi, 0
	s_add_i32 m0, s30, 0x14000
	s_nop 0
	global_load_lds_dwordx4 v130, vcc
	s_add_i32 m0, s30, 0x16000
	s_nop 0
	global_load_lds_dwordx4 v134, vcc
	s_add_u32 vcc_lo, vcc_lo, 0x58000
	s_addc_u32 vcc_hi, vcc_hi, 0
	s_add_i32 m0, s30, 0x15000
	s_nop 0
	global_load_lds_dwordx4 v130, vcc
	s_add_i32 m0, s30, 0x17000
	s_nop 0
	global_load_lds_dwordx4 v134, vcc
	ds_read_b128 v[144:147], v185 offset:32768
	ds_read_b128 v[148:151], v185 offset:33792
	ds_read_b128 v[152:155], v185 offset:34816
	ds_read_b128 v[156:159], v185 offset:35840
	ds_read_b128 v[160:163], v186 offset:32768
	ds_read_b128 v[164:167], v186 offset:33792
	ds_read_b128 v[168:171], v186 offset:34816
	ds_read_b128 v[172:175], v186 offset:35840
	ds_read_b128 v[176:179], v187 offset:32768
	ds_read_b128 v[190:193], v187 offset:33792
	ds_read_b128 v[194:197], v187 offset:34816
	ds_read_b128 v[198:201], v187 offset:35840
	ds_read_b128 v[202:205], v187 offset:36864
	ds_read_b128 v[206:209], v187 offset:37888
	ds_read_b128 v[210:213], v187 offset:38912
	ds_read_b128 v[214:217], v187 offset:39936
	ds_read_b128 v[220:223], v187 offset:49152
	ds_read_b128 v[224:227], v187 offset:50176
	ds_read_b128 v[228:231], v187 offset:51200
	ds_read_b128 v[232:235], v187 offset:52224
	ds_read_b128 v[236:239], v187 offset:53248
	ds_read_b128 v[240:243], v187 offset:54272
	ds_read_b128 v[244:247], v187 offset:55296
	ds_read_b128 v[248:251], v187 offset:56320
	s_nop 15
	s_nop 15
	s_waitcnt lgkmcnt(0)
	s_barrier
	s_setprio 1
	v_mfma_f32_16x16x32_bf16 v[72:75], v[144:147], v[176:179], v[72:75]
	v_mfma_f32_16x16x32_bf16 v[76:79], v[152:155], v[176:179], v[76:79]
	v_mfma_f32_16x16x32_bf16 v[96:99], v[144:147], v[194:197], v[96:99]
	v_mfma_f32_16x16x32_bf16 v[100:103], v[152:155], v[194:197], v[100:103]
	v_mfma_f32_16x16x32_bf16 v[120:123], v[144:147], v[202:205], v[120:123]
	v_mfma_f32_16x16x32_bf16 v[124:127], v[152:155], v[202:205], v[124:127]
	v_mfma_f32_16x16x32_bf16 v[92:95], v[144:147], v[210:213], v[92:95]
	v_mfma_f32_16x16x32_bf16 v[84:87], v[152:155], v[210:213], v[84:87]
	v_mfma_f32_16x16x32_bf16 v[72:75], v[148:151], v[190:193], v[72:75]
	v_mfma_f32_16x16x32_bf16 v[76:79], v[156:159], v[190:193], v[76:79]
	v_mfma_f32_16x16x32_bf16 v[96:99], v[148:151], v[198:201], v[96:99]
	v_mfma_f32_16x16x32_bf16 v[100:103], v[156:159], v[198:201], v[100:103]
	v_mfma_f32_16x16x32_bf16 v[120:123], v[148:151], v[206:209], v[120:123]
	v_mfma_f32_16x16x32_bf16 v[124:127], v[156:159], v[206:209], v[124:127]
	v_mfma_f32_16x16x32_bf16 v[92:95], v[148:151], v[214:217], v[92:95]
	v_mfma_f32_16x16x32_bf16 v[84:87], v[156:159], v[214:217], v[84:87]
	s_setprio 0
	s_setprio 1
	v_mfma_f32_16x16x32_bf16 v[80:83], v[160:163], v[176:179], v[80:83]
	v_mfma_f32_16x16x32_bf16 v[88:91], v[168:171], v[176:179], v[88:91]
	v_mfma_f32_16x16x32_bf16 v[108:111], v[160:163], v[194:197], v[108:111]
	v_mfma_f32_16x16x32_bf16 v[112:115], v[168:171], v[194:197], v[112:115]
	v_mfma_f32_16x16x32_bf16 v[116:119], v[160:163], v[202:205], v[116:119]
	v_mfma_f32_16x16x32_bf16 v[104:107], v[168:171], v[202:205], v[104:107]
	v_mfma_f32_16x16x32_bf16 v[68:71], v[160:163], v[210:213], v[68:71]
	v_mfma_f32_16x16x32_bf16 v[64:67], v[168:171], v[210:213], v[64:67]
	v_mfma_f32_16x16x32_bf16 v[80:83], v[164:167], v[190:193], v[80:83]
	v_mfma_f32_16x16x32_bf16 v[88:91], v[172:175], v[190:193], v[88:91]
	v_mfma_f32_16x16x32_bf16 v[108:111], v[164:167], v[198:201], v[108:111]
	v_mfma_f32_16x16x32_bf16 v[112:115], v[172:175], v[198:201], v[112:115]
	v_mfma_f32_16x16x32_bf16 v[116:119], v[164:167], v[206:209], v[116:119]
	v_mfma_f32_16x16x32_bf16 v[104:107], v[172:175], v[206:209], v[104:107]
	v_mfma_f32_16x16x32_bf16 v[68:71], v[164:167], v[214:217], v[68:71]
	v_mfma_f32_16x16x32_bf16 v[64:67], v[172:175], v[214:217], v[64:67]
	s_setprio 0
	s_setprio 1
	v_mfma_f32_16x16x32_bf16 v[60:63], v[144:147], v[220:223], v[60:63]
	v_mfma_f32_16x16x32_bf16 v[56:59], v[152:155], v[220:223], v[56:59]
	v_mfma_f32_16x16x32_bf16 v[44:47], v[144:147], v[228:231], v[44:47]
	v_mfma_f32_16x16x32_bf16 v[40:43], v[152:155], v[228:231], v[40:43]
	v_mfma_f32_16x16x32_bf16 v[28:31], v[144:147], v[236:239], v[28:31]
	v_mfma_f32_16x16x32_bf16 v[24:27], v[152:155], v[236:239], v[24:27]
	v_mfma_f32_16x16x32_bf16 v[12:15], v[144:147], v[244:247], v[12:15]
	v_mfma_f32_16x16x32_bf16 v[8:11], v[152:155], v[244:247], v[8:11]
	v_mfma_f32_16x16x32_bf16 v[60:63], v[148:151], v[224:227], v[60:63]
	v_mfma_f32_16x16x32_bf16 v[56:59], v[156:159], v[224:227], v[56:59]
	v_mfma_f32_16x16x32_bf16 v[44:47], v[148:151], v[232:235], v[44:47]
	v_mfma_f32_16x16x32_bf16 v[40:43], v[156:159], v[232:235], v[40:43]
	v_mfma_f32_16x16x32_bf16 v[28:31], v[148:151], v[240:243], v[28:31]
	v_mfma_f32_16x16x32_bf16 v[24:27], v[156:159], v[240:243], v[24:27]
	v_mfma_f32_16x16x32_bf16 v[12:15], v[148:151], v[248:251], v[12:15]
	v_mfma_f32_16x16x32_bf16 v[8:11], v[156:159], v[248:251], v[8:11]
	s_setprio 0
	s_setprio 1
	v_mfma_f32_16x16x32_bf16 v[52:55], v[160:163], v[220:223], v[52:55]
	v_mfma_f32_16x16x32_bf16 v[48:51], v[168:171], v[220:223], v[48:51]
	v_mfma_f32_16x16x32_bf16 v[36:39], v[160:163], v[228:231], v[36:39]
	v_mfma_f32_16x16x32_bf16 v[32:35], v[168:171], v[228:231], v[32:35]
	v_mfma_f32_16x16x32_bf16 v[20:23], v[160:163], v[236:239], v[20:23]
	v_mfma_f32_16x16x32_bf16 v[16:19], v[168:171], v[236:239], v[16:19]
	v_mfma_f32_16x16x32_bf16 v[4:7], v[160:163], v[244:247], v[4:7]
	v_mfma_f32_16x16x32_bf16 v[0:3], v[168:171], v[244:247], v[0:3]
	v_mfma_f32_16x16x32_bf16 v[52:55], v[164:167], v[224:227], v[52:55]
	v_mfma_f32_16x16x32_bf16 v[48:51], v[172:175], v[224:227], v[48:51]
	v_mfma_f32_16x16x32_bf16 v[36:39], v[164:167], v[232:235], v[36:39]
	v_mfma_f32_16x16x32_bf16 v[32:35], v[172:175], v[232:235], v[32:35]
	v_mfma_f32_16x16x32_bf16 v[20:23], v[164:167], v[240:243], v[20:23]
	v_mfma_f32_16x16x32_bf16 v[16:19], v[172:175], v[240:243], v[16:19]
	v_mfma_f32_16x16x32_bf16 v[4:7], v[164:167], v[248:251], v[4:7]
	v_mfma_f32_16x16x32_bf16 v[0:3], v[172:175], v[248:251], v[0:3]
	s_setprio 0
	s_waitcnt vmcnt(0)
	s_barrier
	s_add_i32 s56, s56, 2
	s_add_u32 s46, s46, 0x100
	s_addc_u32 s47, s47, 0
	s_cmpk_gt_u32 s56, 0x55
	s_mov_b64 s[22:23], s[24:25]
	s_cbranch_scc0 .LBB0_940
	s_branch .Lk64_done_p7
.Lk64_trail_p7:
	s_add_u32 vcc_lo, s22, 0x80
	s_addc_u32 vcc_hi, s23, 0
	s_add_i32 m0, s30, 0xa000
	s_nop 0
	global_load_lds_dwordx4 v132, vcc
	s_add_u32 vcc_lo, vcc_lo, 0x58000
	s_addc_u32 vcc_hi, vcc_hi, 0
	s_add_i32 m0, s30, 0x9000
	s_nop 0
	global_load_lds_dwordx4 v128, vcc
	s_add_u32 vcc_lo, vcc_lo, 0x108000
	s_addc_u32 vcc_hi, vcc_hi, 0
	s_add_i32 m0, s30, 0xe000
	s_nop 0
	global_load_lds_dwordx4 v132, vcc
	s_add_u32 vcc_lo, vcc_lo, 0x58000
	s_addc_u32 vcc_hi, vcc_hi, 0
	s_add_i32 m0, s30, 0xd000
	s_nop 0
	global_load_lds_dwordx4 v128, vcc
	s_add_u32 vcc_lo, s28, 0x0
	s_addc_u32 vcc_hi, s29, 0
	s_mov_b32 m0, s30
	s_nop 0
	global_load_lds_dwordx4 v128, vcc
	s_sub_u32 vcc_lo, vcc_lo, 0x58000
	s_subb_u32 vcc_hi, vcc_hi, 0
	s_sub_i32 m0, s30, 0x1000
	s_nop 0
	global_load_lds_dwordx4 v128, vcc
	s_add_u32 vcc_lo, vcc_lo, 0x1b8000
	s_addc_u32 vcc_hi, vcc_hi, 0
	s_add_i32 m0, s30, 0x4000
	s_nop 0
	global_load_lds_dwordx4 v128, vcc
	s_sub_u32 vcc_lo, vcc_lo, 0x58000
	s_subb_u32 vcc_hi, vcc_hi, 0
	s_add_i32 m0, s30, 0x3000
	s_nop 0
	global_load_lds_dwordx4 v128, vcc
	s_add_i32 vcc_lo, s56, -22
	s_and_b32 vcc_lo, vcc_lo, 62
	s_lshl_b32 vcc_lo, vcc_lo, 2
	s_lshr_b32 vcc_hi, s30, 10
	s_add_i32 vcc_lo, vcc_lo, vcc_hi
	s_lshl_b32 vcc_hi, s54, 8
	s_add_i32 vcc_lo, vcc_lo, vcc_hi
	s_lshl_b32 vcc_lo, vcc_lo, 13
	s_lshl_b32 vcc_hi, s55, 10
	s_add_i32 vcc_lo, vcc_lo, vcc_hi
	s_add_u32 vcc_lo, s14, vcc_lo
	s_addc_u32 vcc_hi, s15, 0
	v_and_b32_e32 v248, 15, v252
	v_lshlrev_b32_e32 v248, 6, v248
	s_lshr_b32 m0, s30, 2
	s_add_i32 m0, m0, 0x20000
	s_nop 0
	global_load_lds_dword v248, vcc
	ds_read_b128 v[144:147], v185 offset:0
	ds_read_b128 v[148:151], v185 offset:1024
	ds_read_b128 v[152:155], v185 offset:2048
	ds_read_b128 v[156:159], v185 offset:3072
	ds_read_b128 v[160:163], v186 offset:0
	ds_read_b128 v[164:167], v186 offset:1024
	ds_read_b128 v[168:171], v186 offset:2048
	ds_read_b128 v[172:175], v186 offset:3072
	ds_read_b128 v[176:179], v187 offset:0
	ds_read_b128 v[190:193], v187 offset:1024
	ds_read_b128 v[194:197], v187 offset:2048
	ds_read_b128 v[198:201], v187 offset:3072
	ds_read_b128 v[202:205], v187 offset:4096
	ds_read_b128 v[206:209], v187 offset:5120
	ds_read_b128 v[210:213], v187 offset:6144
	ds_read_b128 v[214:217], v187 offset:7168
	ds_read_b128 v[220:223], v187 offset:16384
	ds_read_b128 v[224:227], v187 offset:17408
	ds_read_b128 v[228:231], v187 offset:18432
	ds_read_b128 v[232:235], v187 offset:19456
	ds_read_b128 v[236:239], v187 offset:20480
	ds_read_b128 v[240:243], v187 offset:21504
	ds_read_b128 v[244:247], v187 offset:22528
	ds_read_b128 v[248:251], v187 offset:23552
	s_nop 15
	s_nop 15
	s_waitcnt lgkmcnt(0)
	s_barrier
	s_setprio 1
	v_mfma_f32_16x16x32_bf16 v[72:75], v[144:147], v[176:179], v[72:75]
	v_mfma_f32_16x16x32_bf16 v[76:79], v[152:155], v[176:179], v[76:79]
	v_mfma_f32_16x16x32_bf16 v[96:99], v[144:147], v[194:197], v[96:99]
	v_mfma_f32_16x16x32_bf16 v[100:103], v[152:155], v[194:197], v[100:103]
	v_mfma_f32_16x16x32_bf16 v[120:123], v[144:147], v[202:205], v[120:123]
	v_mfma_f32_16x16x32_bf16 v[124:127], v[152:155], v[202:205], v[124:127]
	v_mfma_f32_16x16x32_bf16 v[92:95], v[144:147], v[210:213], v[92:95]
	v_mfma_f32_16x16x32_bf16 v[84:87], v[152:155], v[210:213], v[84:87]
	v_mfma_f32_16x16x32_bf16 v[72:75], v[148:151], v[190:193], v[72:75]
	v_mfma_f32_16x16x32_bf16 v[76:79], v[156:159], v[190:193], v[76:79]
	v_mfma_f32_16x16x32_bf16 v[96:99], v[148:151], v[198:201], v[96:99]
	v_mfma_f32_16x16x32_bf16 v[100:103], v[156:159], v[198:201], v[100:103]
	v_mfma_f32_16x16x32_bf16 v[120:123], v[148:151], v[206:209], v[120:123]
	v_mfma_f32_16x16x32_bf16 v[124:127], v[156:159], v[206:209], v[124:127]
	v_mfma_f32_16x16x32_bf16 v[92:95], v[148:151], v[214:217], v[92:95]
	v_mfma_f32_16x16x32_bf16 v[84:87], v[156:159], v[214:217], v[84:87]
	s_setprio 0
	s_setprio 1
	v_mfma_f32_16x16x32_bf16 v[80:83], v[160:163], v[176:179], v[80:83]
	v_mfma_f32_16x16x32_bf16 v[88:91], v[168:171], v[176:179], v[88:91]
	v_mfma_f32_16x16x32_bf16 v[108:111], v[160:163], v[194:197], v[108:111]
	v_mfma_f32_16x16x32_bf16 v[112:115], v[168:171], v[194:197], v[112:115]
	v_mfma_f32_16x16x32_bf16 v[116:119], v[160:163], v[202:205], v[116:119]
	v_mfma_f32_16x16x32_bf16 v[104:107], v[168:171], v[202:205], v[104:107]
	v_mfma_f32_16x16x32_bf16 v[68:71], v[160:163], v[210:213], v[68:71]
	v_mfma_f32_16x16x32_bf16 v[64:67], v[168:171], v[210:213], v[64:67]
	v_mfma_f32_16x16x32_bf16 v[80:83], v[164:167], v[190:193], v[80:83]
	v_mfma_f32_16x16x32_bf16 v[88:91], v[172:175], v[190:193], v[88:91]
	v_mfma_f32_16x16x32_bf16 v[108:111], v[164:167], v[198:201], v[108:111]
	v_mfma_f32_16x16x32_bf16 v[112:115], v[172:175], v[198:201], v[112:115]
	v_mfma_f32_16x16x32_bf16 v[116:119], v[164:167], v[206:209], v[116:119]
	v_mfma_f32_16x16x32_bf16 v[104:107], v[172:175], v[206:209], v[104:107]
	v_mfma_f32_16x16x32_bf16 v[68:71], v[164:167], v[214:217], v[68:71]
	v_mfma_f32_16x16x32_bf16 v[64:67], v[172:175], v[214:217], v[64:67]
	s_setprio 0
	s_setprio 1
	v_mfma_f32_16x16x32_bf16 v[60:63], v[144:147], v[220:223], v[60:63]
	v_mfma_f32_16x16x32_bf16 v[56:59], v[152:155], v[220:223], v[56:59]
	v_mfma_f32_16x16x32_bf16 v[44:47], v[144:147], v[228:231], v[44:47]
	v_mfma_f32_16x16x32_bf16 v[40:43], v[152:155], v[228:231], v[40:43]
	v_mfma_f32_16x16x32_bf16 v[28:31], v[144:147], v[236:239], v[28:31]
	v_mfma_f32_16x16x32_bf16 v[24:27], v[152:155], v[236:239], v[24:27]
	v_mfma_f32_16x16x32_bf16 v[12:15], v[144:147], v[244:247], v[12:15]
	v_mfma_f32_16x16x32_bf16 v[8:11], v[152:155], v[244:247], v[8:11]
	v_mfma_f32_16x16x32_bf16 v[60:63], v[148:151], v[224:227], v[60:63]
	v_mfma_f32_16x16x32_bf16 v[56:59], v[156:159], v[224:227], v[56:59]
	v_mfma_f32_16x16x32_bf16 v[44:47], v[148:151], v[232:235], v[44:47]
	v_mfma_f32_16x16x32_bf16 v[40:43], v[156:159], v[232:235], v[40:43]
	v_mfma_f32_16x16x32_bf16 v[28:31], v[148:151], v[240:243], v[28:31]
	v_mfma_f32_16x16x32_bf16 v[24:27], v[156:159], v[240:243], v[24:27]
	v_mfma_f32_16x16x32_bf16 v[12:15], v[148:151], v[248:251], v[12:15]
	v_mfma_f32_16x16x32_bf16 v[8:11], v[156:159], v[248:251], v[8:11]
	s_setprio 0
	s_setprio 1
	v_mfma_f32_16x16x32_bf16 v[52:55], v[160:163], v[220:223], v[52:55]
	v_mfma_f32_16x16x32_bf16 v[48:51], v[168:171], v[220:223], v[48:51]
	v_mfma_f32_16x16x32_bf16 v[36:39], v[160:163], v[228:231], v[36:39]
	v_mfma_f32_16x16x32_bf16 v[32:35], v[168:171], v[228:231], v[32:35]
	v_mfma_f32_16x16x32_bf16 v[20:23], v[160:163], v[236:239], v[20:23]
	v_mfma_f32_16x16x32_bf16 v[16:19], v[168:171], v[236:239], v[16:19]
	v_mfma_f32_16x16x32_bf16 v[4:7], v[160:163], v[244:247], v[4:7]
	v_mfma_f32_16x16x32_bf16 v[0:3], v[168:171], v[244:247], v[0:3]
	v_mfma_f32_16x16x32_bf16 v[52:55], v[164:167], v[224:227], v[52:55]
	v_mfma_f32_16x16x32_bf16 v[48:51], v[172:175], v[224:227], v[48:51]
	v_mfma_f32_16x16x32_bf16 v[36:39], v[164:167], v[232:235], v[36:39]
	v_mfma_f32_16x16x32_bf16 v[32:35], v[172:175], v[232:235], v[32:35]
	v_mfma_f32_16x16x32_bf16 v[20:23], v[164:167], v[240:243], v[20:23]
	v_mfma_f32_16x16x32_bf16 v[16:19], v[172:175], v[240:243], v[16:19]
	v_mfma_f32_16x16x32_bf16 v[4:7], v[164:167], v[248:251], v[4:7]
	v_mfma_f32_16x16x32_bf16 v[0:3], v[172:175], v[248:251], v[0:3]
	s_setprio 0
	s_waitcnt vmcnt(1)
	s_barrier
	s_add_u32 vcc_lo, s28, 0x0
	s_addc_u32 vcc_hi, s29, 0
	s_add_i32 m0, s30, 0x2000
	s_nop 0
	global_load_lds_dwordx4 v132, vcc
	s_add_u32 vcc_lo, vcc_lo, 0x58000
	s_addc_u32 vcc_hi, vcc_hi, 0
	s_add_i32 m0, s30, 0x1000
	s_nop 0
	global_load_lds_dwordx4 v128, vcc
	s_add_u32 vcc_lo, vcc_lo, 0x108000
	s_addc_u32 vcc_hi, vcc_hi, 0
	s_add_i32 m0, s30, 0x6000
	s_nop 0
	global_load_lds_dwordx4 v132, vcc
	s_add_u32 vcc_lo, vcc_lo, 0x58000
	s_addc_u32 vcc_hi, vcc_hi, 0
	s_add_i32 m0, s30, 0x5000
	s_nop 0
	global_load_lds_dwordx4 v128, vcc
	s_add_u32 vcc_lo, s28, 0x80
	s_addc_u32 vcc_hi, s29, 0
	s_add_i32 m0, s30, 0x8000
	s_nop 0
	global_load_lds_dwordx4 v128, vcc
	s_sub_u32 vcc_lo, vcc_lo, 0x58000
	s_subb_u32 vcc_hi, vcc_hi, 0
	s_add_i32 m0, s30, 0x7000
	s_nop 0
	global_load_lds_dwordx4 v128, vcc
	s_add_u32 vcc_lo, vcc_lo, 0x1b8000
	s_addc_u32 vcc_hi, vcc_hi, 0
	s_add_i32 m0, s30, 0xc000
	s_nop 0
	global_load_lds_dwordx4 v128, vcc
	s_sub_u32 vcc_lo, vcc_lo, 0x58000
	s_subb_u32 vcc_hi, vcc_hi, 0
	s_add_i32 m0, s30, 0xb000
	s_nop 0
	global_load_lds_dwordx4 v128, vcc
	ds_read_b128 v[144:147], v185 offset:32768
	ds_read_b128 v[148:151], v185 offset:33792
	ds_read_b128 v[152:155], v185 offset:34816
	ds_read_b128 v[156:159], v185 offset:35840
	ds_read_b128 v[160:163], v186 offset:32768
	ds_read_b128 v[164:167], v186 offset:33792
	ds_read_b128 v[168:171], v186 offset:34816
	ds_read_b128 v[172:175], v186 offset:35840
	ds_read_b128 v[176:179], v187 offset:32768
	ds_read_b128 v[190:193], v187 offset:33792
	ds_read_b128 v[194:197], v187 offset:34816
	ds_read_b128 v[198:201], v187 offset:35840
	ds_read_b128 v[202:205], v187 offset:36864
	ds_read_b128 v[206:209], v187 offset:37888
	ds_read_b128 v[210:213], v187 offset:38912
	ds_read_b128 v[214:217], v187 offset:39936
	ds_read_b128 v[220:223], v187 offset:49152
	ds_read_b128 v[224:227], v187 offset:50176
	ds_read_b128 v[228:231], v187 offset:51200
	ds_read_b128 v[232:235], v187 offset:52224
	ds_read_b128 v[236:239], v187 offset:53248
	ds_read_b128 v[240:243], v187 offset:54272
	ds_read_b128 v[244:247], v187 offset:55296
	ds_read_b128 v[248:251], v187 offset:56320
	s_nop 15
	s_nop 15
	s_waitcnt lgkmcnt(0)
	s_barrier
	s_setprio 1
	v_mfma_f32_16x16x32_bf16 v[72:75], v[144:147], v[176:179], v[72:75]
	v_mfma_f32_16x16x32_bf16 v[76:79], v[152:155], v[176:179], v[76:79]
	v_mfma_f32_16x16x32_bf16 v[96:99], v[144:147], v[194:197], v[96:99]
	v_mfma_f32_16x16x32_bf16 v[100:103], v[152:155], v[194:197], v[100:103]
	v_mfma_f32_16x16x32_bf16 v[120:123], v[144:147], v[202:205], v[120:123]
	v_mfma_f32_16x16x32_bf16 v[124:127], v[152:155], v[202:205], v[124:127]
	v_mfma_f32_16x16x32_bf16 v[92:95], v[144:147], v[210:213], v[92:95]
	v_mfma_f32_16x16x32_bf16 v[84:87], v[152:155], v[210:213], v[84:87]
	v_mfma_f32_16x16x32_bf16 v[72:75], v[148:151], v[190:193], v[72:75]
	v_mfma_f32_16x16x32_bf16 v[76:79], v[156:159], v[190:193], v[76:79]
	v_mfma_f32_16x16x32_bf16 v[96:99], v[148:151], v[198:201], v[96:99]
	v_mfma_f32_16x16x32_bf16 v[100:103], v[156:159], v[198:201], v[100:103]
	v_mfma_f32_16x16x32_bf16 v[120:123], v[148:151], v[206:209], v[120:123]
	v_mfma_f32_16x16x32_bf16 v[124:127], v[156:159], v[206:209], v[124:127]
	v_mfma_f32_16x16x32_bf16 v[92:95], v[148:151], v[214:217], v[92:95]
	v_mfma_f32_16x16x32_bf16 v[84:87], v[156:159], v[214:217], v[84:87]
	s_setprio 0
	s_setprio 1
	v_mfma_f32_16x16x32_bf16 v[80:83], v[160:163], v[176:179], v[80:83]
	v_mfma_f32_16x16x32_bf16 v[88:91], v[168:171], v[176:179], v[88:91]
	v_mfma_f32_16x16x32_bf16 v[108:111], v[160:163], v[194:197], v[108:111]
	v_mfma_f32_16x16x32_bf16 v[112:115], v[168:171], v[194:197], v[112:115]
	v_mfma_f32_16x16x32_bf16 v[116:119], v[160:163], v[202:205], v[116:119]
	v_mfma_f32_16x16x32_bf16 v[104:107], v[168:171], v[202:205], v[104:107]
	v_mfma_f32_16x16x32_bf16 v[68:71], v[160:163], v[210:213], v[68:71]
	v_mfma_f32_16x16x32_bf16 v[64:67], v[168:171], v[210:213], v[64:67]
	v_mfma_f32_16x16x32_bf16 v[80:83], v[164:167], v[190:193], v[80:83]
	v_mfma_f32_16x16x32_bf16 v[88:91], v[172:175], v[190:193], v[88:91]
	v_mfma_f32_16x16x32_bf16 v[108:111], v[164:167], v[198:201], v[108:111]
	v_mfma_f32_16x16x32_bf16 v[112:115], v[172:175], v[198:201], v[112:115]
	v_mfma_f32_16x16x32_bf16 v[116:119], v[164:167], v[206:209], v[116:119]
	v_mfma_f32_16x16x32_bf16 v[104:107], v[172:175], v[206:209], v[104:107]
	v_mfma_f32_16x16x32_bf16 v[68:71], v[164:167], v[214:217], v[68:71]
	v_mfma_f32_16x16x32_bf16 v[64:67], v[172:175], v[214:217], v[64:67]
	s_setprio 0
	s_setprio 1
	v_mfma_f32_16x16x32_bf16 v[60:63], v[144:147], v[220:223], v[60:63]
	v_mfma_f32_16x16x32_bf16 v[56:59], v[152:155], v[220:223], v[56:59]
	v_mfma_f32_16x16x32_bf16 v[44:47], v[144:147], v[228:231], v[44:47]
	v_mfma_f32_16x16x32_bf16 v[40:43], v[152:155], v[228:231], v[40:43]
	v_mfma_f32_16x16x32_bf16 v[28:31], v[144:147], v[236:239], v[28:31]
	v_mfma_f32_16x16x32_bf16 v[24:27], v[152:155], v[236:239], v[24:27]
	v_mfma_f32_16x16x32_bf16 v[12:15], v[144:147], v[244:247], v[12:15]
	v_mfma_f32_16x16x32_bf16 v[8:11], v[152:155], v[244:247], v[8:11]
	v_mfma_f32_16x16x32_bf16 v[60:63], v[148:151], v[224:227], v[60:63]
	v_mfma_f32_16x16x32_bf16 v[56:59], v[156:159], v[224:227], v[56:59]
	v_mfma_f32_16x16x32_bf16 v[44:47], v[148:151], v[232:235], v[44:47]
	v_mfma_f32_16x16x32_bf16 v[40:43], v[156:159], v[232:235], v[40:43]
	v_mfma_f32_16x16x32_bf16 v[28:31], v[148:151], v[240:243], v[28:31]
	v_mfma_f32_16x16x32_bf16 v[24:27], v[156:159], v[240:243], v[24:27]
	v_mfma_f32_16x16x32_bf16 v[12:15], v[148:151], v[248:251], v[12:15]
	v_mfma_f32_16x16x32_bf16 v[8:11], v[156:159], v[248:251], v[8:11]
	s_setprio 0
	s_setprio 1
	v_mfma_f32_16x16x32_bf16 v[52:55], v[160:163], v[220:223], v[52:55]
	v_mfma_f32_16x16x32_bf16 v[48:51], v[168:171], v[220:223], v[48:51]
	v_mfma_f32_16x16x32_bf16 v[36:39], v[160:163], v[228:231], v[36:39]
	v_mfma_f32_16x16x32_bf16 v[32:35], v[168:171], v[228:231], v[32:35]
	v_mfma_f32_16x16x32_bf16 v[20:23], v[160:163], v[236:239], v[20:23]
	v_mfma_f32_16x16x32_bf16 v[16:19], v[168:171], v[236:239], v[16:19]
	v_mfma_f32_16x16x32_bf16 v[4:7], v[160:163], v[244:247], v[4:7]
	v_mfma_f32_16x16x32_bf16 v[0:3], v[168:171], v[244:247], v[0:3]
	v_mfma_f32_16x16x32_bf16 v[52:55], v[164:167], v[224:227], v[52:55]
	v_mfma_f32_16x16x32_bf16 v[48:51], v[172:175], v[224:227], v[48:51]
	v_mfma_f32_16x16x32_bf16 v[36:39], v[164:167], v[232:235], v[36:39]
	v_mfma_f32_16x16x32_bf16 v[32:35], v[172:175], v[232:235], v[32:35]
	v_mfma_f32_16x16x32_bf16 v[20:23], v[164:167], v[240:243], v[20:23]
	v_mfma_f32_16x16x32_bf16 v[16:19], v[172:175], v[240:243], v[16:19]
	v_mfma_f32_16x16x32_bf16 v[4:7], v[164:167], v[248:251], v[4:7]
	v_mfma_f32_16x16x32_bf16 v[0:3], v[172:175], v[248:251], v[0:3]
	s_setprio 0
	s_waitcnt vmcnt(0)
	s_barrier
	s_add_i32 s56, s56, 2
	s_add_u32 s46, s46, 0x100
	s_addc_u32 s47, s47, 0
	s_cmpk_gt_u32 s56, 0x55
	s_mov_b64 s[22:23], s[24:25]
	s_cbranch_scc0 .LBB0_940
